# mLSTM chunk loop: also the 4-MFMA transposed-read segment after the second barrier reads all operands up front (both copies)
# baseline (speedup 1.0000x reference)
.LBB0_686:
	v_mov_b32_e32 v0, s78
	v_add_u32_e32 v173, s76, v141
	s_waitcnt lgkmcnt(0)
	ds_read_b64 v[56:57], v0
	ds_read_b64_tr_b16 v[0:1], v168 offset:17408
	ds_read_b64_tr_b16 v[2:3], v169 offset:18432
	ds_read_b64_tr_b16 v[4:5], v173 offset:33792
	ds_read_b64_tr_b16 v[6:7], v173 offset:34048
	ds_read_b64_tr_b16 v[58:59], v168 offset:21504
	ds_read_b64_tr_b16 v[60:61], v169 offset:22528
	ds_read_b64_tr_b16 v[62:63], v173 offset:35840
	ds_read_b64_tr_b16 v[64:65], v173 offset:36096
	ds_read_b64_tr_b16 v[180:181], v168 offset:25600
	ds_read_b64_tr_b16 v[182:183], v169 offset:26624
	ds_read_b64_tr_b16 v[184:185], v173 offset:37888
	ds_read_b64_tr_b16 v[186:187], v173 offset:38144
	ds_read_b64_tr_b16 v[188:189], v168 offset:29696
	ds_read_b64_tr_b16 v[190:191], v169 offset:30720
	s_waitcnt lgkmcnt(10)
	v_mfma_f32_32x32x16_bf16 v[0:15], v[0:3], v[4:7], 0
	ds_read_b64_tr_b16 v[192:193], v173 offset:39936
	ds_read_b64_tr_b16 v[194:195], v173 offset:40192
	s_waitcnt lgkmcnt(8)
	v_mfma_f32_32x32x16_bf16 v[0:15], v[58:61], v[62:65], v[0:15]
	s_waitcnt lgkmcnt(4)
	v_mfma_f32_32x32x16_bf16 v[0:15], v[180:183], v[184:187], v[0:15]
	s_waitcnt lgkmcnt(0)
	v_mfma_f32_32x32x16_bf16 v[0:15], v[188:191], v[192:195], v[0:15]
	v_mov_b32_e32 v58, 0
	s_and_saveexec_b64 s[4:5], s[6:7]
	s_cbranch_execz .LBB0_688
	ds_read_b32 v58, v145
	ds_read_b32 v59, v146
	s_waitcnt lgkmcnt(0)
	v_pk_mul_f32 v[58:59], v[56:57], v[58:59]
	s_nop 0
	v_add_f32_e32 v58, v58, v59

.LBB0_714:
	v_mov_b32_e32 v0, s3
	s_waitcnt lgkmcnt(0)
	ds_read_b64 v[56:57], v0
	ds_read_b64_tr_b16 v[0:1], v168 offset:17408
	ds_read_b64_tr_b16 v[2:3], v169 offset:18432
	ds_read_b64_tr_b16 v[4:5], v173 offset:33792
	ds_read_b64_tr_b16 v[6:7], v173 offset:34048
	ds_read_b64_tr_b16 v[58:59], v168 offset:21504
	ds_read_b64_tr_b16 v[60:61], v169 offset:22528
	ds_read_b64_tr_b16 v[62:63], v173 offset:35840
	ds_read_b64_tr_b16 v[64:65], v173 offset:36096
	ds_read_b64_tr_b16 v[180:181], v168 offset:25600
	ds_read_b64_tr_b16 v[182:183], v169 offset:26624
	ds_read_b64_tr_b16 v[184:185], v173 offset:37888
	ds_read_b64_tr_b16 v[186:187], v173 offset:38144
	ds_read_b64_tr_b16 v[188:189], v168 offset:29696
	ds_read_b64_tr_b16 v[190:191], v169 offset:30720
	s_waitcnt lgkmcnt(10)
	v_mfma_f32_32x32x16_bf16 v[0:15], v[0:3], v[4:7], 0
	ds_read_b64_tr_b16 v[192:193], v173 offset:39936
	ds_read_b64_tr_b16 v[194:195], v173 offset:40192
	s_waitcnt lgkmcnt(8)
	v_mfma_f32_32x32x16_bf16 v[0:15], v[58:61], v[62:65], v[0:15]
	s_waitcnt lgkmcnt(4)
	v_mfma_f32_32x32x16_bf16 v[0:15], v[180:183], v[184:187], v[0:15]
	s_waitcnt lgkmcnt(0)
	v_mfma_f32_32x32x16_bf16 v[0:15], v[188:191], v[192:195], v[0:15]
	v_mov_b32_e32 v58, 0
	s_and_saveexec_b64 s[56:57], s[6:7]
	s_cbranch_execz .LBB0_716
	ds_read_b32 v58, v145
	ds_read_b32 v59, v146
	s_waitcnt lgkmcnt(0)
	v_pk_mul_f32 v[58:59], v[56:57], v[58:59]
	s_nop 0
	v_add_f32_e32 v58, v58, v59
